# adds: hgrn_finish 16-lane reduction by DPP adds instead of four ds_bpermute round trips
# speedup vs baseline: 1.0050x; 1.0050x over previous
; __device__ __forceinline__ float siluf_(float x) { return x * __builtin_amdgcn_rcpf(1.f + __expf(-x)); }
; __device__ __forceinline__ u32x4 pack8(f32x4 a, f32x4 b) { u32x4 w; w.x = cvtpk(a[0], a[1]); w.y = cvtpk(a[2], a[3]); w.z = cvtpk(b[0], b[1]); w.w = cvtpk(b[2], b[3]); return w; }
; __device__ __forceinline__ void unpack8(u32x4 w, f32x4& a, f32x4& b) { a = (f32x4){bflo(w.x), bfhi(w.x), bflo(w.y), bfhi(w.y)}; b = (f32x4){bflo(w.z), bfhi(w.z), bflo(w.w), bfhi(w.w)}; }
; __device__ __forceinline__ void hgrn_finish(bf16_t* Pm, const float* normw) {
;     ...
;     for (int t = gw; t < T; t += NGW) {
;         bf16_t* op = Pm + (size_t)t * PW + PC_HI + lane * 8; const bf16_t* gp = Pm + (size_t)t * PW + PC_HG + lane * 8;
;         f32x4 a, b, g0, g1; unpack8(*(const u32x4*)op, a, b); unpack8(*(const u32x4*)gp, g0, g1);
;         float ss = (a[0] * a[0] + a[1] * a[1]) + (a[2] * a[2] + a[3] * a[3]) + (b[0] * b[0] + b[1] * b[1]) + (b[2] * b[2] + b[3] * b[3]);
;         ss += __shfl_xor(ss, 1); ss += __shfl_xor(ss, 2); ss += __shfl_xor(ss, 4); ss += __shfl_xor(ss, 8);
;         const float rs = __builtin_amdgcn_rsqf(ss * (1.f / 128.f) + EPS);
; #pragma unroll
;         for (int j = 0; j < 4; ++j) { a[j] = a[j] * rs * w0[j] * siluf_(g0[j]); b[j] = b[j] * rs * w1[j] * siluf_(g1[j]); }
;         *(u32x4*)op = pack8(a, b);
;     }
.Lhf_nopf:
	v_lshlrev_b32_e32 v24, 16, v19
	v_lshlrev_b32_e32 v26, 16, v23
	v_and_b32_e32 v25, 0xffff0000, v19
	v_mul_f32_e32 v19, 0xbfb8aa3b, v26
	v_exp_f32_e32 v19, v19
	v_and_b32_e32 v27, 0xffff0000, v23
	v_lshlrev_b32_e32 v30, 16, v21
	v_and_b32_e32 v31, 0xffff0000, v21
	v_add_f32_e32 v19, 1.0, v19
	v_rcp_f32_e32 v28, v19
	v_mul_f32_e32 v19, 0xbfb8aa3b, v27
	v_exp_f32_e32 v19, v19
	v_mov_b32_e32 v34, v25
	v_add_f32_e32 v19, 1.0, v19
	v_rcp_f32_e32 v29, v19
	v_and_b32_e32 v19, 0xffff0000, v22
	v_pk_mul_f32 v[26:27], v[28:29], v[26:27]
	v_lshlrev_b32_e32 v28, 16, v17
	v_and_b32_e32 v29, 0xffff0000, v17
	v_mul_f32_e32 v17, 0xbfb8aa3b, v30
	v_exp_f32_e32 v17, v17
	v_mov_b32_e32 v37, v29
	v_mov_b32_e32 v21, v28
	v_add_f32_e32 v17, 1.0, v17
	v_rcp_f32_e32 v32, v17
	v_mul_f32_e32 v17, 0xbfb8aa3b, v31
	v_exp_f32_e32 v17, v17
	s_nop 0
	v_add_f32_e32 v17, 1.0, v17
	v_rcp_f32_e32 v33, v17
	s_nop 0
	v_pk_mul_f32 v[30:31], v[32:33], v[30:31]
	v_lshlrev_b32_e32 v32, 16, v18
	v_and_b32_e32 v33, 0xffff0000, v18
	v_lshlrev_b32_e32 v18, 16, v22
	v_mul_f32_e32 v17, 0xbfb8aa3b, v18
	v_exp_f32_e32 v17, v17
	v_mov_b32_e32 v35, v33
	v_mov_b32_e32 v22, v24
	v_mov_b32_e32 v23, v32
	v_pk_mul_f32 v[34:35], v[34:35], v[34:35]
	v_add_f32_e32 v17, 1.0, v17
	v_pk_fma_f32 v[22:23], v[22:23], v[22:23], v[34:35]
	v_rcp_f32_e32 v34, v17
	v_mul_f32_e32 v17, 0xbfb8aa3b, v19
	v_exp_f32_e32 v17, v17
	s_nop 0
	v_add_f32_e32 v17, 1.0, v17
	v_rcp_f32_e32 v35, v17
	v_and_b32_e32 v17, 0xffff0000, v20
	v_pk_mul_f32 v[18:19], v[34:35], v[18:19]
	v_and_b32_e32 v35, 0xffff0000, v16
	v_lshlrev_b32_e32 v34, 16, v16
	v_mov_b32_e32 v36, v35
	v_lshlrev_b32_e32 v16, 16, v20
	v_mov_b32_e32 v20, v34
	v_pk_mul_f32 v[36:37], v[36:37], v[36:37]
	s_nop 0
	v_pk_fma_f32 v[20:21], v[20:21], v[20:21], v[36:37]
	v_mul_f32_e32 v36, 0xbfb8aa3b, v16
	v_add_f32_e32 v20, v20, v21
	v_add_f32_e32 v20, v23, v20
	v_add_f32_e32 v20, v22, v20
	v_mul_f32_e32 v37, 0xbfb8aa3b, v17
	v_exp_f32_e32 v36, v36
	v_add_f32_dpp v20, v20, v20 quad_perm:[1,0,3,2] row_mask:0xf bank_mask:0xf
	v_exp_f32_e32 v37, v37
	v_add_f32_e32 v36, 1.0, v36
	v_add_f32_dpp v20, v20, v20 quad_perm:[2,3,0,1] row_mask:0xf bank_mask:0xf
	v_add_f32_e32 v37, 1.0, v37
	v_rcp_f32_e32 v36, v36
	v_add_f32_dpp v20, v20, v20 row_half_mirror row_mask:0xf bank_mask:0xf
	v_rcp_f32_e32 v37, v37
	s_nop 0
	v_add_f32_dpp v20, v20, v20 row_mirror row_mask:0xf bank_mask:0xf
	v_pk_mul_f32 v[16:17], v[36:37], v[16:17]
	v_fmamk_f32 v20, v20, 0x3c000000, v236
	v_rsq_f32_e32 v20, v20
	s_nop 0
	v_pk_mul_f32 v[22:23], v[20:21], v[34:35] op_sel_hi:[0,1]
	v_pk_mul_f32 v[22:23], v[4:5], v[22:23]
	s_nop 0
	v_pk_mul_f32 v[16:17], v[16:17], v[22:23]
	v_pk_mul_f32 v[22:23], v[20:21], v[32:33] op_sel_hi:[0,1]
	v_pk_mul_f32 v[22:23], v[8:9], v[22:23]
	v_cvt_pk_bf16_f32 v16, v16, v17
	v_pk_mul_f32 v[18:19], v[18:19], v[22:23]
	v_pk_mul_f32 v[22:23], v[20:21], v[28:29] op_sel_hi:[0,1]
	v_pk_mul_f32 v[20:21], v[20:21], v[24:25] op_sel_hi:[0,1]
	v_pk_mul_f32 v[22:23], v[6:7], v[22:23]
	v_pk_mul_f32 v[20:21], v[10:11], v[20:21]
	v_pk_mul_f32 v[22:23], v[30:31], v[22:23]
	v_pk_mul_f32 v[20:21], v[26:27], v[20:21]
	v_cvt_pk_bf16_f32 v17, v22, v23
	v_cvt_pk_bf16_f32 v18, v18, v19
	v_cvt_pk_bf16_f32 v19, v20, v21
	global_store_dwordx4 v[0:1], v[16:19], off
	v_mov_b32_e32 v0, v48
	v_mov_b32_e32 v1, v49
	s_waitcnt vmcnt(1)
	v_mov_b32_e32 v16, v40
	v_mov_b32_e32 v17, v41
	v_mov_b32_e32 v18, v42
	v_mov_b32_e32 v19, v43
	v_mov_b32_e32 v20, v44
	v_mov_b32_e32 v21, v45
	v_mov_b32_e32 v22, v46
	v_mov_b32_e32 v23, v47
	s_andn2_b64 exec, exec, s[8:9]
	s_cbranch_execnz .LBB0_815
